# MLA attention loop: row max on raw scores, V tile row-major in LDS with ds_read_b64_tr_b16, PV fragment addresses precomputed
# speedup vs baseline: 1.0413x; 1.0079x over previous
; template <int MODE>
; DI void attn_unit(LAS unsigned char* lds, const AttnArgs a) {
;     ...
;     ATT_LOAD(it0);
;     ATT_STORE(0);
;     __syncthreads();
;     if (it0 + 1 < ntile) ATT_LOAD(it0 + 1);
.LBB0_139:
	s_or_b64 exec, exec, s[8:9]
	v_and_b32_e32 v3, 2, v2
	v_lshlrev_b32_e32 v3, 1, v3
	v_xor_b32_e32 v0, v0, v3
	v_lshlrev_b32_e32 v0, 4, v0
	v_lshl_or_b32 v0, v2, 7, v0
	v_add_u32_e32 v143, 0x100, v0
	s_cmpk_lt_i32 s4, 0xff41
	s_waitcnt vmcnt(0)
	ds_write_b128 v143, v[128:131] offset:13312
	s_waitcnt lgkmcnt(0)
	s_barrier
	s_cbranch_scc1 .LBB0_153
	s_and_saveexec_b64 s[8:9], s[10:11]
	s_cbranch_execz .LBB0_146
	v_add_u32_e32 v0, v15, v14
	v_mul_lo_u32 v3, v0, 12
	v_add_u32_e32 v6, 64, v0
	v_sub_u32_e32 v3, v12, v3
	v_ashrrev_i32_e32 v7, 31, v6
	v_lshl_add_u64 v[6:7], v[6:7], 0, s[66:67]
	v_cmp_gt_i32_e32 vcc, 8, v3
	v_lshlrev_b32_e32 v0, 3, v3
	s_and_saveexec_b64 s[14:15], vcc
	s_xor_b64 s[14:15], exec, s[14:15]
	v_lshlrev_b64 v[6:7], 11, v[6:7]
	v_lshl_add_u64 v[6:7], s[6:7], 0, v[6:7]
	v_ashrrev_i32_e32 v9, 31, v0
	v_mov_b32_e32 v8, v0
	v_lshl_add_u64 v[8:9], v[8:9], 1, v[6:7]
	s_andn2_saveexec_b64 s[14:15], s[14:15]
	s_cbranch_execz .LBB0_145
	v_readlane_b32 s16, v255, 13
	v_readlane_b32 s17, v255, 14
	s_nop 1
	v_mov_b64_e32 v[8:9], s[16:17]
	v_mad_u64_u32 v[8:9], s[16:17], v6, s86, v[8:9]
	v_mad_i32_i24 v9, v7, s86, v9
	s_movk_i32 s16, 0xff80
	v_lshl_add_u64 v[6:7], v[0:1], 1, v[8:9]
	s_mov_b32 s17, -1
	v_lshl_add_u64 v[8:9], v[6:7], 0, s[16:17]

; #define LAS __attribute__((address_space(3)))
; template <int MODE>
; DI void attn_unit(LAS unsigned char* lds, const AttnArgs a) {
;     ...
;     f32x16 o[NDB];
; #pragma unroll
;     for (int d = 0; d < NDB; ++d)
; #pragma unroll
;         for (int i = 0; i < 16; ++i) o[d][i] = 0.f;
;     float mrow = -1e30f, lrow = 0.f, carry = 1.f;
;     int ntile;
;     if (MODE == 0) ntile = a.nk / 64; else if (MODE == 1) ntile = (a.q0 + 255) / 64 + 1; else if (MODE == 2) ntile = (a.q0 + 254) / 64 + 1; else ntile = 6;
;     const int it0 = (MODE == 3 && a.q0 == 0) ? 2 : 0;
;     constexpr int NKC = (64 * (DK / 8) + 511) / 512, NVC = (64 * (DV / 8) + 511) / 512;
;     u32x4 kreg[NKC], vreg[NVC];
;     ...
;     ATT_LOAD(it0);
;     ATT_STORE(0);
;     __syncthreads();
;     if (it0 + 1 < ntile) ATT_LOAD(it0 + 1);
;     bool sb_dead = false;
;     for (int it = it0; it < ntile; ++it) {
;         const int kbase = ATT_KBASE(it), cur = (it - it0) & 1;
;         const LAS bf16_t* Kc = Ks + cur * BUFE; const LAS bf16_t* Vc = Vt + cur * BUFE;
;         bool active = true;
;         if (MODE == 1) active = kbase <= q0w + 31;
;         if (MODE == 2) active = (kbase <= q0w + 30) && !sb_dead;
;     ...
;         const bf16x8 pb00 = pack8(s0, 0), pb01 = pack8(s0, 1), pb10 = pack8(s1, 0), pb11 = pack8(s1, 1);
; #pragma unroll
;         for (int d = 0; d < NDB; ++d) {
;             const LAS bf16_t* vp = Vc + (d * 32 + r32) * VLD;
;             const int sw = SWZ ? ((((d * 32 + r32) >> 3) & 7) << 2) : 0;
.LBB0_153:
	s_mov_b64 s[8:9], -1
	s_cmpk_gt_i32 s4, 0xfec1
	v_lshlrev_b32_e32 v198, 2, v48
	s_cbranch_scc0 .LBB0_184
	v_lshlrev_b32_e32 v142, 2, v48
	v_lshl_add_u64 v[144:145], v[4:5], 1, s[6:7]
	v_lshrrev_b32_e32 v4, 1, v12
	v_and_b32_e32 v5, 12, v4
	v_bitop3_b32 v200, v142, v4, 12 bitop3:0x78
	v_or_b32_e32 v4, 32, v13
	v_or_b32_e32 v3, 8, v142
	v_lshrrev_b32_e32 v4, 1, v4
	v_or_b32_e32 v6, 16, v142
	v_or_b32_e32 v7, 24, v142
	v_or_b32_e32 v8, 32, v142
	v_or_b32_e32 v9, 40, v142
	v_or_b32_e32 v10, 48, v142
	v_or_b32_e32 v11, 56, v142
	v_bitop3_b32 v215, v4, v3, 28 bitop3:0x6c
	v_add_u32_e32 v3, v15, v14
	v_bitop3_b32 v214, v4, v142, 28 bitop3:0x6c
	v_bitop3_b32 v216, v4, v6, 28 bitop3:0x6c
	v_bitop3_b32 v217, v4, v7, 28 bitop3:0x6c
	v_bitop3_b32 v218, v4, v8, 28 bitop3:0x6c
	v_bitop3_b32 v219, v4, v9, 28 bitop3:0x6c
	v_bitop3_b32 v220, v4, v10, 28 bitop3:0x6c
	v_bitop3_b32 v221, v4, v11, 28 bitop3:0x6c
	v_mul_lo_u32 v4, v3, 12
	s_movk_i32 s8, 0x90
	v_sub_u32_e32 v4, v12, v4
	v_add_u32_e32 v6, v52, v51
	v_bitop3_b32 v201, v142, v5, 8 bitop3:0x36
	v_bitop3_b32 v205, v142, v5, 16 bitop3:0x36
	v_bitop3_b32 v208, v142, v5, 24 bitop3:0x36
	v_bitop3_b32 v209, v142, v5, 32 bitop3:0x36
	v_bitop3_b32 v210, v142, v5, 40 bitop3:0x36
	v_bitop3_b32 v211, v142, v5, 48 bitop3:0x36
	v_bitop3_b32 v212, v142, v5, 56 bitop3:0x36
	v_mad_u32_u24 v213, v13, s8, v238
	s_movk_i32 s8, 0xd0
	v_lshlrev_b32_e32 v223, 4, v4
	v_mul_lo_u32 v5, v6, 12
	v_cmp_gt_i32_e64 s[14:15], 8, v4
	v_lshlrev_b32_e32 v4, 3, v4
	v_mul_lo_u32 v222, v3, s8
	v_sub_u32_e32 v7, v50, v5
	v_mul_lo_u32 v224, v6, s8
	v_ashrrev_i32_e32 v5, 31, v4
	v_readlane_b32 s8, v255, 13
	v_lshl_add_u64 v[146:147], v[4:5], 1, s[6:7]
	v_mov_b32_e32 v5, v1
	v_readlane_b32 s9, v255, 14
	s_sub_i32 s0, 0xfff, s0
	s_ashr_i32 s4, s0, 31
	v_lshl_add_u64 v[148:149], v[4:5], 1, s[8:9]
	v_lshlrev_b32_e32 v4, 3, v7
	v_ashrrev_i32_e32 v5, 31, v4
	s_lshr_b32 s4, s4, 26
	v_lshl_add_u64 v[150:151], v[4:5], 1, s[6:7]
	v_mov_b32_e32 v5, v1
	s_add_i32 s0, s0, s4
	v_mul_u32_u24_e32 v0, 0xd0, v13
	v_lshl_add_u64 v[152:153], v[4:5], 1, s[8:9]
	v_lshlrev_b32_e32 v4, 1, v49
	s_movk_i32 s6, 0x100
	v_mov_b32_e32 v14, v1
	v_mov_b32_e32 v15, v1
	s_ashr_i32 s0, s0, 6
	v_mul_u32_u24_e32 v199, 0x90, v13
	v_lshlrev_b32_e32 v225, 4, v7
	v_cmp_gt_i32_e64 s[16:17], 8, v7
	v_add3_u32 v226, s6, v0, v4
	v_add_u32_e32 v227, 0x80, v3
	v_add_u32_e32 v228, 0x80, v6
	v_add_u32_e32 v229, 0x80, v2
	v_mov_b32_e32 v0, v1
	v_mov_b32_e32 v2, v1
	v_mov_b32_e32 v3, v1
	v_mov_b32_e32 v4, v1
	v_mov_b32_e32 v6, v1
	v_mov_b32_e32 v7, v1
	v_mov_b32_e32 v8, v1
	v_mov_b32_e32 v9, v1
	v_mov_b32_e32 v10, v1
	v_mov_b32_e32 v11, v1
	v_mov_b32_e32 v12, v1
	v_mov_b32_e32 v13, v1
	v_mov_b64_e32 v[30:31], v[14:15]
	v_mov_b64_e32 v[46:47], v[14:15]
	s_or_b32 s4, s19, 31
	s_mov_b32 s5, 0
	s_max_i32 s20, s0, 0
	v_mov_b32_e32 v135, v134
	v_mov_b32_e32 v230, 0
	v_mov_b32_e32 v232, 0xf149f2ca
	v_mov_b64_e32 v[28:29], v[12:13]
	v_mov_b64_e32 v[26:27], v[10:11]
	v_mov_b64_e32 v[24:25], v[8:9]
	v_mov_b64_e32 v[22:23], v[6:7]
	v_mov_b64_e32 v[20:21], v[4:5]
	v_mov_b64_e32 v[18:19], v[2:3]
	v_mov_b64_e32 v[16:17], v[0:1]
	v_mov_b64_e32 v[44:45], v[12:13]
	v_mov_b64_e32 v[42:43], v[10:11]
	v_mov_b64_e32 v[40:41], v[8:9]
	v_mov_b64_e32 v[38:39], v[6:7]
	v_mov_b64_e32 v[36:37], v[4:5]
	v_mov_b64_e32 v[34:35], v[2:3]
	v_mov_b64_e32 v[32:33], v[0:1]
	v_and_b32_e32 v214, 63, v202
	v_and_b32_e32 v215, 3, v214
	v_bfe_u32 v216, v214, 2, 2
	v_bfe_u32 v217, v214, 4, 1
	v_bfe_u32 v218, v214, 5, 1
	v_lshrrev_b32_e32 v219, 1, v215
	v_lshl_or_b32 v219, v217, 1, v219
	v_and_b32_e32 v220, 2, v216
	v_lshl_or_b32 v219, v220, 1, v219
	v_lshlrev_b32_e32 v219, 4, v219
	v_and_b32_e32 v215, 1, v215
	v_lshl_or_b32 v219, v215, 3, v219
	v_lshl_or_b32 v219, v216, 7, v219
	v_lshl_or_b32 v200, v218, 9, v219
	v_xor_b32_e32 v201, 64, v200
	s_mov_b32 s21, 0
	s_and_b32 s8, s21, 1
	s_cmp_gt_i32 s5, s4
	s_cbranch_scc0 .LBB0_156

; #define LAS __attribute__((address_space(3)))
; DI float ex2(float x) { return __builtin_amdgcn_exp2f(x); }
; DI float max3f(float a, float b, float c) { float r; asm("v_max3_f32 %0, %1, %2, %3" : "=v"(r) : "v"(a), "v"(b), "v"(c)); return r; }
; #define MFMA32(a, b, c) __builtin_amdgcn_mfma_f32_32x32x16_bf16((a), (b), (c), 0, 0, 0)
; template <int MODE>
; DI void attn_unit(LAS unsigned char* lds, const AttnArgs a) {
;     ...
;         f32x16 s0, s1;
; #pragma unroll
;         for (int i = 0; i < 16; ++i) { s0[i] = 0.f; s1[i] = 0.f; }
; #pragma unroll
;         for (int ks = 0; ks < NKS; ++ks) {
;             const bf16x8 a0 = *(const LAS bf16x8*)(Kc + r32 * KLD + ks * 16 + 8 * hh);
;             const bf16x8 a1 = *(const LAS bf16x8*)(Kc + (32 + r32) * KLD + ks * 16 + 8 * hh);
;             s0 = MFMA32(a0, qf[ks], s0); s1 = MFMA32(a1, qf[ks], s1);
;         }
;         if (MODE == 2) {
;             if (kbase + 63 < q0w) { sb_block<false>(s1, kbase + 32, qi, hh, a.c2, carry); sb_block<false>(s0, kbase, qi, hh, a.c2, carry); }
;             else                  { sb_block<true>(s1, kbase + 32, qi, hh, a.c2, carry);  sb_block<true>(s0, kbase, qi, hh, a.c2, carry); }
;         } else {
;             const bool interior = (MODE == 0) || (MODE == 1 && kbase + 63 <= q0w);
;             float mnew, alpha, ls = 0.f;
;             if (interior) {
; #pragma unroll
;                 for (int i = 0; i < 16; ++i) { s0[i] *= a.c2; s1[i] *= a.c2; }
;                 float mx = max3f(s0[0], s1[0], s0[1]);
;                 mx = max3f(mx, s1[1], s0[2]); mx = max3f(mx, s1[2], s0[3]); mx = max3f(mx, s1[3], s0[4]); mx = max3f(mx, s1[4], s0[5]);
;                 mx = max3f(mx, s1[5], s0[6]); mx = max3f(mx, s1[6], s0[7]); mx = max3f(mx, s1[7], s0[8]); mx = max3f(mx, s1[8], s0[9]);
;                 mx = max3f(mx, s1[9], s0[10]); mx = max3f(mx, s1[10], s0[11]); mx = max3f(mx, s1[11], s0[12]); mx = max3f(mx, s1[12], s0[13]);
;                 mx = max3f(mx, s1[13], s0[14]); mx = max3f(mx, s1[14], s0[15]); mx = fmaxf(mx, s1[15]);
;                 mx = fmaxf(mx, __shfl_xor(mx, 32));
;                 mnew = fmaxf(mrow, mx); alpha = ex2(mrow - mnew);
; #pragma unroll
;                 for (int i = 0; i < 16; ++i) {
;                     const float p0 = ex2(s0[i] - mnew), p1 = ex2(s1[i] - mnew);
;                     s0[i] = p0; s1[i] = p1; ls += p0 + p1;
;                 }
.LBB0_156:
	s_mul_i32 s9, s8, 0x2c00
	v_lshl_add_u32 v0, s9, 1, v226
	ds_read_b128 v[2:5], v0 offset:6656
	ds_read_b128 v[6:9], v0
	ds_read_b128 v[10:13], v0 offset:32
	s_add_i32 s22, s5, 63
	s_mov_b64 s[6:7], -1
	s_waitcnt lgkmcnt(2)
	v_mfma_f32_32x32x16_bf16 v[80:95], v[2:5], v[96:99], 0
	ds_read_b128 v[2:5], v0 offset:6688
	s_cmp_gt_i32 s22, s19
	s_waitcnt lgkmcnt(2)
	v_mfma_f32_32x32x16_bf16 v[48:63], v[6:9], v[96:99], 0
	s_waitcnt lgkmcnt(1)
	v_mfma_f32_32x32x16_bf16 v[48:63], v[10:13], v[100:103], v[48:63]
	s_waitcnt lgkmcnt(0)
	v_mfma_f32_32x32x16_bf16 v[80:95], v[2:5], v[100:103], v[80:95]
	ds_read_b128 v[2:5], v0 offset:64
	ds_read_b128 v[6:9], v0 offset:6720
	s_waitcnt lgkmcnt(1)
	v_mfma_f32_32x32x16_bf16 v[48:63], v[2:5], v[104:107], v[48:63]
	s_waitcnt lgkmcnt(0)
	v_mfma_f32_32x32x16_bf16 v[80:95], v[6:9], v[104:107], v[80:95]
	ds_read_b128 v[2:5], v0 offset:96
	ds_read_b128 v[6:9], v0 offset:6752
	s_waitcnt lgkmcnt(1)
	v_mfma_f32_32x32x16_bf16 v[48:63], v[2:5], v[108:111], v[48:63]
	s_waitcnt lgkmcnt(0)
	v_mfma_f32_32x32x16_bf16 v[80:95], v[6:9], v[108:111], v[80:95]
	ds_read_b128 v[2:5], v0 offset:128
	ds_read_b128 v[6:9], v0 offset:6784
	s_waitcnt lgkmcnt(1)
	v_mfma_f32_32x32x16_bf16 v[48:63], v[2:5], v[112:115], v[48:63]
	s_waitcnt lgkmcnt(0)
	v_mfma_f32_32x32x16_bf16 v[80:95], v[6:9], v[112:115], v[80:95]
	ds_read_b128 v[2:5], v0 offset:160
	ds_read_b128 v[6:9], v0 offset:6816
	s_waitcnt lgkmcnt(1)
	v_mfma_f32_32x32x16_bf16 v[48:63], v[2:5], v[116:119], v[48:63]
	s_waitcnt lgkmcnt(0)
	v_mfma_f32_32x32x16_bf16 v[80:95], v[6:9], v[116:119], v[80:95]
	s_nop 9
	v_mul_f32_e32 v5, 0x3e16c740, v48
	v_mul_f32_e32 v3, 0x3e16c740, v49
	s_cbranch_scc1 .LBB0_182
	v_max3_f32 v0, v48, v80, v49
	v_max3_f32 v0, v0, v81, v50
	v_max3_f32 v0, v0, v82, v51
	v_max3_f32 v0, v0, v83, v52
	v_max3_f32 v0, v0, v84, v53
	v_max3_f32 v0, v0, v85, v54
	v_max3_f32 v0, v0, v86, v55
	v_max3_f32 v0, v0, v87, v56
	v_max3_f32 v0, v0, v88, v57
	v_max3_f32 v0, v0, v89, v58
	v_max3_f32 v0, v0, v90, v59
	v_max3_f32 v0, v0, v91, v60
	v_max3_f32 v0, v0, v92, v61
	v_max3_f32 v0, v0, v93, v62
	v_max3_f32 v0, v0, v94, v63
	v_and_b32_e32 v4, 64, v243
	v_xor_b32_e32 v2, 32, v243
	v_add_u32_e32 v4, 64, v4
	v_cmp_lt_i32_e32 vcc, v2, v4
	v_max_f32_e32 v0, v0, v95
	v_mul_f32_e32 v0, 0x3e16c740, v0
	v_cndmask_b32_e32 v2, v243, v2, vcc
	v_lshlrev_b32_e32 v2, 2, v2
	ds_bpermute_b32 v2, v2, v0
	s_mov_b32 s6, 0x3e16c740
	s_waitcnt lgkmcnt(0)
	v_max3_f32 v231, v232, v0, v2
	v_fma_f32 v0, v48, s6, -v231
	v_exp_f32_e32 v64, v0
	v_fma_f32 v0, v80, s6, -v231
	v_exp_f32_e32 v233, v0
	v_fma_f32 v0, v49, s6, -v231
	v_exp_f32_e32 v48, v0
	v_fma_f32 v0, v81, s6, -v231
	v_exp_f32_e32 v0, v0
	v_add_f32_e32 v49, v64, v233
	v_fma_f32 v2, v50, s6, -v231
	v_exp_f32_e32 v4, v2
	v_pk_add_f32 v[6:7], v[48:49], v[0:1]
	v_fma_f32 v2, v82, s6, -v231
	v_pk_add_f32 v[160:161], v[6:7], v[6:7] op_sel_hi:[0,1]
	v_fma_f32 v6, v51, s6, -v231
	v_exp_f32_e32 v2, v2
	v_exp_f32_e32 v166, v6
	v_fma_f32 v6, v83, s6, -v231
	v_exp_f32_e32 v160, v6
	v_add_f32_e32 v167, v4, v2
	v_mov_b32_e32 v65, v48
	v_pk_add_f32 v[6:7], v[166:167], v[160:161]
	s_nop 0
	v_pk_add_f32 v[164:165], v[6:7], v[6:7] op_sel_hi:[0,1]
	v_fma_f32 v7, v84, s6, -v231
	v_fma_f32 v6, v52, s6, -v231
	v_exp_f32_e32 v8, v7
	v_fma_f32 v7, v53, s6, -v231
	v_exp_f32_e32 v6, v6
	v_exp_f32_e32 v172, v7
	v_fma_f32 v7, v85, s6, -v231
	v_exp_f32_e32 v164, v7
	v_add_f32_e32 v173, v6, v8
	v_fma_f32 v7, v54, s6, -v231
	v_pk_add_f32 v[10:11], v[172:173], v[164:165]
	s_nop 0
	v_pk_add_f32 v[170:171], v[10:11], v[10:11] op_sel_hi:[0,1]
	v_exp_f32_e32 v10, v7
	v_fma_f32 v7, v86, s6, -v231
	v_exp_f32_e32 v14, v7
	v_fma_f32 v7, v55, s6, -v231
	v_exp_f32_e32 v176, v7
	v_fma_f32 v7, v87, s6, -v231
	v_exp_f32_e32 v170, v7
	v_add_f32_e32 v177, v10, v14
	v_fma_f32 v7, v56, s6, -v231
	v_pk_add_f32 v[12:13], v[176:177], v[170:171]
	s_nop 0
	v_pk_add_f32 v[174:175], v[12:13], v[12:13] op_sel_hi:[0,1]
	v_exp_f32_e32 v12, v7
	v_fma_f32 v7, v88, s6, -v231
	v_exp_f32_e32 v154, v7
	v_fma_f32 v7, v57, s6, -v231
	v_exp_f32_e32 v182, v7
	v_fma_f32 v7, v89, s6, -v231
	v_exp_f32_e32 v174, v7
	v_fma_f32 v7, v58, s6, -v231
	v_add_f32_e32 v183, v12, v154
	v_exp_f32_e32 v158, v7
	v_fma_f32 v7, v90, s6, -v231
	v_pk_add_f32 v[66:67], v[182:183], v[174:175]
	v_exp_f32_e32 v156, v7
	v_fma_f32 v7, v59, s6, -v231
	v_pk_add_f32 v[180:181], v[66:67], v[66:67] op_sel_hi:[0,1]
	v_exp_f32_e32 v188, v7
	v_fma_f32 v7, v91, s6, -v231
	v_exp_f32_e32 v180, v7
	v_fma_f32 v7, v60, s6, -v231
	v_add_f32_e32 v189, v158, v156
	v_exp_f32_e32 v168, v7
	v_fma_f32 v7, v92, s6, -v231
	v_pk_add_f32 v[66:67], v[188:189], v[180:181]
	v_exp_f32_e32 v162, v7
	v_fma_f32 v7, v61, s6, -v231
	v_pk_add_f32 v[186:187], v[66:67], v[66:67] op_sel_hi:[0,1]
	v_exp_f32_e32 v192, v7
	v_fma_f32 v7, v93, s6, -v231
	v_exp_f32_e32 v186, v7
	v_fma_f32 v7, v62, s6, -v231
	v_add_f32_e32 v193, v168, v162
	v_exp_f32_e32 v184, v7
	v_fma_f32 v7, v94, s6, -v231
	v_pk_add_f32 v[66:67], v[192:193], v[186:187]
	v_exp_f32_e32 v178, v7
	v_fma_f32 v7, v63, s6, -v231
	v_pk_add_f32 v[190:191], v[66:67], v[66:67] op_sel_hi:[0,1]
	v_exp_f32_e32 v194, v7
	v_fma_f32 v7, v95, s6, -v231
	v_exp_f32_e32 v190, v7
	v_add_f32_e32 v195, v184, v178
	v_pk_add_f32 v[66:67], v[194:195], v[190:191]
	s_nop 0
	v_add_f32_e32 v161, v66, v67
	s_cbranch_execz .LBB0_183

; #define LAS __attribute__((address_space(3)))
; #define MFMA32(a, b, c) __builtin_amdgcn_mfma_f32_32x32x16_bf16((a), (b), (c), 0, 0, 0)
; #define VFRAG(off) __builtin_shufflevector(*(const LAS s16x4*)(vp + (((off) + 4 * hh) ^ sw)), *(const LAS s16x4*)(vp + (((off) + 8 + 4 * hh) ^ sw)), 0, 1, 2, 3, 4, 5, 6, 7)
; template <int MODE>
; DI void attn_unit(LAS unsigned char* lds, const AttnArgs a) {
;     ...
;         const bf16x8 pb00 = pack8(s0, 0), pb01 = pack8(s0, 1), pb10 = pack8(s1, 0), pb11 = pack8(s1, 1);
; #pragma unroll
;         for (int d = 0; d < NDB; ++d) {
;             const LAS bf16_t* vp = Vc + (d * 32 + r32) * VLD;
;             const int sw = SWZ ? ((((d * 32 + r32) >> 3) & 7) << 2) : 0;
;     ...
;             o[d] = MFMA32(VFRAG(0), pb00, o[d]);
;             o[d] = MFMA32(VFRAG(16), pb01, o[d]);
;             o[d] = MFMA32(VFRAG(32), pb10, o[d]);
;             o[d] = MFMA32(VFRAG(48), pb11, o[d]);
;     ...
;         }
.LBB0_160:
	s_cmp_lg_u32 s9, 0
	s_cbranch_scc1 .Lmla_pv1
	v_cvt_pk_bf16_f32 v50, v6, v172
	v_cvt_pk_bf16_f32 v6, v233, v0
	v_cvt_pk_bf16_f32 v9, v14, v170
	ds_read_b64_tr_b16 v[52:53], v200 offset:13568
	ds_read_b64_tr_b16 v[54:55], v200 offset:14592
	v_fmac_f32_e32 v161, v230, v48
	v_cvt_pk_bf16_f32 v48, v64, v65
	v_cvt_pk_bf16_f32 v49, v4, v166
	v_cvt_pk_bf16_f32 v51, v10, v176
	v_cvt_pk_bf16_f32 v10, v12, v182
	s_waitcnt lgkmcnt(0)
	v_mfma_f32_32x32x16_bf16 v[32:47], v[52:55], v[48:51], v[32:47]
	ds_read_b64_tr_b16 v[52:53], v200 offset:15616
	ds_read_b64_tr_b16 v[54:55], v200 offset:16640
	v_cvt_pk_bf16_f32 v11, v158, v188
	v_cvt_pk_bf16_f32 v12, v168, v192
	v_cvt_pk_bf16_f32 v13, v184, v194
	v_cvt_pk_bf16_f32 v7, v2, v160
	s_waitcnt lgkmcnt(0)
	v_mfma_f32_32x32x16_bf16 v[32:47], v[52:55], v[10:13], v[32:47]
	ds_read_b64_tr_b16 v[52:53], v200 offset:17664
	ds_read_b64_tr_b16 v[54:55], v200 offset:18688
	v_cvt_pk_bf16_f32 v8, v8, v164
	v_cvt_pk_bf16_f32 v2, v154, v174
	s_waitcnt lgkmcnt(0)
	v_mfma_f32_32x32x16_bf16 v[32:47], v[52:55], v[6:9], v[32:47]
	ds_read_b64_tr_b16 v[52:53], v200 offset:19712
	ds_read_b64_tr_b16 v[54:55], v200 offset:20736
	v_cvt_pk_bf16_f32 v3, v156, v180
	v_cvt_pk_bf16_f32 v4, v162, v186
	v_cvt_pk_bf16_f32 v5, v178, v190
	v_mov_b32_e32 v230, v161
	s_waitcnt lgkmcnt(0)
	v_mfma_f32_32x32x16_bf16 v[32:47], v[52:55], v[2:5], v[32:47]
	ds_read_b64_tr_b16 v[52:53], v201 offset:13568
	ds_read_b64_tr_b16 v[54:55], v201 offset:14592
	s_waitcnt lgkmcnt(0)
	v_mfma_f32_32x32x16_bf16 v[16:31], v[52:55], v[48:51], v[16:31]
	ds_read_b64_tr_b16 v[48:49], v201 offset:15616
	ds_read_b64_tr_b16 v[50:51], v201 offset:16640
	s_waitcnt lgkmcnt(0)
	v_mfma_f32_32x32x16_bf16 v[16:31], v[48:51], v[10:13], v[16:31]
	ds_read_b64_tr_b16 v[10:11], v201 offset:17664
	ds_read_b64_tr_b16 v[12:13], v201 offset:18688
	s_waitcnt lgkmcnt(0)
	v_mfma_f32_32x32x16_bf16 v[16:31], v[10:13], v[6:9], v[16:31]
	ds_read_b64_tr_b16 v[6:7], v201 offset:19712
	ds_read_b64_tr_b16 v[8:9], v201 offset:20736
	s_waitcnt lgkmcnt(0)
	v_mfma_f32_32x32x16_bf16 v[16:31], v[6:9], v[2:5], v[16:31]
	s_branch .Lmla_pvj
.Lmla_pv1:
	v_cvt_pk_bf16_f32 v50, v6, v172
	v_cvt_pk_bf16_f32 v6, v233, v0
	v_cvt_pk_bf16_f32 v9, v14, v170
	ds_read_b64_tr_b16 v[52:53], v200 offset:36096
	ds_read_b64_tr_b16 v[54:55], v200 offset:37120
	v_fmac_f32_e32 v161, v230, v48
	v_cvt_pk_bf16_f32 v48, v64, v65
	v_cvt_pk_bf16_f32 v49, v4, v166
	v_cvt_pk_bf16_f32 v51, v10, v176
	v_cvt_pk_bf16_f32 v10, v12, v182
	s_waitcnt lgkmcnt(0)
	v_mfma_f32_32x32x16_bf16 v[32:47], v[52:55], v[48:51], v[32:47]
	ds_read_b64_tr_b16 v[52:53], v200 offset:38144
	ds_read_b64_tr_b16 v[54:55], v200 offset:39168
	v_cvt_pk_bf16_f32 v11, v158, v188
	v_cvt_pk_bf16_f32 v12, v168, v192
	v_cvt_pk_bf16_f32 v13, v184, v194
	v_cvt_pk_bf16_f32 v7, v2, v160
	s_waitcnt lgkmcnt(0)
	v_mfma_f32_32x32x16_bf16 v[32:47], v[52:55], v[10:13], v[32:47]
	ds_read_b64_tr_b16 v[52:53], v200 offset:40192
	ds_read_b64_tr_b16 v[54:55], v200 offset:41216
	v_cvt_pk_bf16_f32 v8, v8, v164
	v_cvt_pk_bf16_f32 v2, v154, v174
	s_waitcnt lgkmcnt(0)
	v_mfma_f32_32x32x16_bf16 v[32:47], v[52:55], v[6:9], v[32:47]
	ds_read_b64_tr_b16 v[52:53], v200 offset:42240
	ds_read_b64_tr_b16 v[54:55], v200 offset:43264
	v_cvt_pk_bf16_f32 v3, v156, v180
	v_cvt_pk_bf16_f32 v4, v162, v186
	v_cvt_pk_bf16_f32 v5, v178, v190
	v_mov_b32_e32 v230, v161
	s_waitcnt lgkmcnt(0)
	v_mfma_f32_32x32x16_bf16 v[32:47], v[52:55], v[2:5], v[32:47]
	ds_read_b64_tr_b16 v[52:53], v201 offset:36096
	ds_read_b64_tr_b16 v[54:55], v201 offset:37120
	s_waitcnt lgkmcnt(0)
	v_mfma_f32_32x32x16_bf16 v[16:31], v[52:55], v[48:51], v[16:31]
	ds_read_b64_tr_b16 v[48:49], v201 offset:38144
	ds_read_b64_tr_b16 v[50:51], v201 offset:39168
	s_waitcnt lgkmcnt(0)
	v_mfma_f32_32x32x16_bf16 v[16:31], v[48:51], v[10:13], v[16:31]
	ds_read_b64_tr_b16 v[10:11], v201 offset:40192
	ds_read_b64_tr_b16 v[12:13], v201 offset:41216
	s_waitcnt lgkmcnt(0)
	v_mfma_f32_32x32x16_bf16 v[16:31], v[10:13], v[6:9], v[16:31]
	ds_read_b64_tr_b16 v[6:7], v201 offset:42240
	ds_read_b64_tr_b16 v[8:9], v201 offset:43264
	s_waitcnt lgkmcnt(0)
	v_mfma_f32_32x32x16_bf16 v[16:31], v[6:9], v[2:5], v[16:31]
.Lmla_pvj:
	s_cmp_ge_i32 s21, s0
	s_cbranch_scc1 .LBB0_166

.LBB0_165:
	s_or_b64 exec, exec, s[6:7]
	v_lshl_add_u32 v0, s8, 1, v143
	s_waitcnt vmcnt(0)
	ds_write_b128 v0, v[128:131] offset:13312
